# stack25 + scan1 next-chunk LoRA compute: four LDS reads and eight MFMAs (four independent accumulators) issued first, then the four sigmoid VALU blocks
# baseline (speedup 1.0000x reference)
; #define LAS __attribute__((address_space(3)))
; __device__ __forceinline__ unsigned f2bf(float f) { return pk2(f, f) & 0xffffu; }
; __device__ __forceinline__ void lds_barrier() { asm volatile("s_waitcnt lgkmcnt(0)" ::: "memory"); __builtin_amdgcn_s_barrier(); asm volatile("" ::: "memory"); }
; __device__ __forceinline__ f32x4 mma16(bf16x8 a, bf16x8 b, f32x4 c) { return __builtin_amdgcn_mfma_f32_16x16x32_bf16(a, b, c, 0, 0, 0); }
; __device__ __forceinline__ v2u pack4(const f32x4 v) { v2u o; o.x = pk2(v[0], v[1]); o.y = pk2(v[2], v[3]); return o; }
; __device__ __forceinline__ void phase_scan1(Frame& F, int l) {
;     ...
;                 if (w < 4) { const v2u qv = *(const LAS v2u*)(QK + (16 * i + fr) * CP + c0); rhs = (f32x4){bf_lo(qv.x), bf_hi(qv.x), bf_lo(qv.y), bf_hi(qv.y)}; }
;                 else rhs = *(const LAS f32x4*)(XF + (16 * i + fr) * XP + c0 - 64);
;                 rhs = rhs - acc;
; #pragma unroll
;                 for (int r = 0; r < 4; ++r) ACCT[(c0 + r) * ATP + fr] = (bf16)f2bf(rhs[r]);
;                 asm volatile("" ::: "memory");
;                 const bf16x8 ta = *(const LAS bf16x8*)(TBt + (16 * i + fr) * TBP + 8 * fq), tb = *(const LAS bf16x8*)(ACCT + (16 * w + fr) * ATP + 8 * fq);
;                 const f32x4 o = mma16(ta, tb, (f32x4){0.f, 0.f, 0.f, 0.f});
;                 *(LAS v2u*)(PT + (16 * w + fr) * CP + 16 * i + 4 * fq) = pack4(o);
;                 asm volatile("" ::: "memory");
;             }
;         }
;         lds_barrier();
.LBB0_577:
	s_waitcnt lgkmcnt(0)
	s_nop 3
	v_sub_f32_e32 v42, v46, v42
	v_sub_f32_e32 v43, v47, v43
	v_cvt_pk_bf16_f32 v42, v42, s0
	v_sub_f32_e32 v0, v49, v45
	v_sub_f32_e32 v44, v48, v44
	ds_write_b16 v52, v42
	v_cvt_pk_bf16_f32 v42, v43, s0
	ds_write_b16 v52, v42 offset:64
	v_cvt_pk_bf16_f32 v42, v44, s0
	v_cvt_pk_bf16_f32 v0, v0, s0
	ds_write_b16 v52, v42 offset:128
	ds_write_b16 v52, v0 offset:192
	ds_read_b128 v[42:45], v57 offset:10240
	ds_read_b128 v[46:49], v54
	s_waitcnt lgkmcnt(0)
	v_mfma_f32_16x16x32_bf16 v[42:45], v[42:45], v[46:49], 0
	s_and_b64 vcc, exec, s[6:7]
	s_nop 6
	v_cvt_pk_bf16_f32 v42, v42, v43
	v_cvt_pk_bf16_f32 v43, v44, v45
	ds_write_b64 v53, v[42:43] offset:96
	s_waitcnt lgkmcnt(0)
	s_barrier
	s_cbranch_vccnz .LBB0_510
	s_lshr_b32 s6, s72, 6
	v_mov_b32_e32 v0, v85
	s_cmpk_lt_i32 s72, 0x1000
	s_cselect_b32 s6, s6, s72
	s_lshl_b32 s6, s6, 8
	v_and_b32_e32 v42, -16, v0
	v_and_or_b32 v0, v0, 15, s97
	s_and_b32 s6, s6, 0xf00
	v_mul_u32_u24_e32 v0, 0x110, v0
	v_add3_u32 v50, v99, s6, v42
	v_add3_u32 v0, v100, v0, v42
	ds_read_b128 v[46:49], v50
	s_waitcnt vmcnt(7)
	v_mfma_f32_16x16x32_bf16 v[42:45], v[10:13], v[2:5], 0
	v_mov_b32_e32 v195, v194
	s_waitcnt vmcnt(6)
	v_mfma_f32_16x16x32_bf16 v[42:45], v[14:17], v[6:9], v[42:45]
	ds_read_b128 v[52:55], v50 offset:64
	s_waitcnt vmcnt(5)
	v_mfma_f32_16x16x32_bf16 v[126:129], v[18:21], v[2:5], 0
	s_waitcnt vmcnt(4)
	v_mfma_f32_16x16x32_bf16 v[126:129], v[22:25], v[6:9], v[126:129]
	ds_read_b128 v[56:59], v50 offset:128
	s_waitcnt vmcnt(3)
	v_mfma_f32_16x16x32_bf16 v[130:133], v[26:29], v[2:5], 0
	s_waitcnt vmcnt(2)
	v_mfma_f32_16x16x32_bf16 v[130:133], v[30:33], v[6:9], v[130:133]
	ds_read_b128 v[60:63], v50 offset:192
	s_waitcnt vmcnt(1)
	v_mfma_f32_16x16x32_bf16 v[134:137], v[34:37], v[2:5], 0
	s_waitcnt vmcnt(0)
	v_mfma_f32_16x16x32_bf16 v[134:137], v[38:41], v[6:9], v[134:137]
	s_waitcnt lgkmcnt(0)
	s_nop 6
	v_add_f32_e32 v42, v42, v46
	v_add_f32_e32 v43, v43, v47
	v_add_f32_e32 v44, v44, v48
	v_add_f32_e32 v45, v45, v49
	v_mul_f32_e32 v42, 0xbfb8aa3b, v42
	v_mul_f32_e32 v43, 0xbfb8aa3b, v43
	v_mul_f32_e32 v44, 0xbfb8aa3b, v44
	v_mul_f32_e32 v45, 0xbfb8aa3b, v45
	v_exp_f32_e32 v42, v42
	v_exp_f32_e32 v43, v43
	v_exp_f32_e32 v44, v44
	v_exp_f32_e32 v45, v45
	v_add_f32_e32 v42, 1.0, v42
	v_add_f32_e32 v43, 1.0, v43
	v_add_f32_e32 v44, 1.0, v44
	v_add_f32_e32 v45, 1.0, v45
	v_rcp_f32_e32 v42, v42
	v_rcp_f32_e32 v43, v43
	v_rcp_f32_e32 v44, v44
	v_rcp_f32_e32 v45, v45
	v_pk_mul_f32 v[42:43], v[196:197], v[42:43]
	v_pk_mul_f32 v[44:45], v[194:195], v[44:45]
	ds_write_b128 v0, v[42:45]
	v_add_f32_e32 v126, v126, v52
	v_add_f32_e32 v127, v127, v53
	v_add_f32_e32 v128, v128, v54
	v_add_f32_e32 v129, v129, v55
	v_mul_f32_e32 v126, 0xbfb8aa3b, v126
	v_mul_f32_e32 v127, 0xbfb8aa3b, v127
	v_mul_f32_e32 v128, 0xbfb8aa3b, v128
	v_mul_f32_e32 v129, 0xbfb8aa3b, v129
	v_exp_f32_e32 v126, v126
	v_exp_f32_e32 v127, v127
	v_exp_f32_e32 v128, v128
	v_exp_f32_e32 v129, v129
	v_add_f32_e32 v126, 1.0, v126
	v_add_f32_e32 v127, 1.0, v127
	v_add_f32_e32 v128, 1.0, v128
	v_add_f32_e32 v129, 1.0, v129
	v_rcp_f32_e32 v126, v126
	v_rcp_f32_e32 v127, v127
	v_rcp_f32_e32 v128, v128
	v_rcp_f32_e32 v129, v129
	v_pk_mul_f32 v[126:127], v[196:197], v[126:127]
	v_pk_mul_f32 v[128:129], v[194:195], v[128:129]
	ds_write_b128 v0, v[126:129] offset:64
	v_add_f32_e32 v130, v130, v56
	v_add_f32_e32 v131, v131, v57
	v_add_f32_e32 v132, v132, v58
	v_add_f32_e32 v133, v133, v59
	v_mul_f32_e32 v130, 0xbfb8aa3b, v130
	v_mul_f32_e32 v131, 0xbfb8aa3b, v131
	v_mul_f32_e32 v132, 0xbfb8aa3b, v132
	v_mul_f32_e32 v133, 0xbfb8aa3b, v133
	v_exp_f32_e32 v130, v130
	v_exp_f32_e32 v131, v131
	v_exp_f32_e32 v132, v132
	v_exp_f32_e32 v133, v133
	v_add_f32_e32 v130, 1.0, v130
	v_add_f32_e32 v131, 1.0, v131
	v_add_f32_e32 v132, 1.0, v132
	v_add_f32_e32 v133, 1.0, v133
	v_rcp_f32_e32 v130, v130
	v_rcp_f32_e32 v131, v131
	v_rcp_f32_e32 v132, v132
	v_rcp_f32_e32 v133, v133
	v_pk_mul_f32 v[130:131], v[196:197], v[130:131]
	v_pk_mul_f32 v[132:133], v[194:195], v[132:133]
	ds_write_b128 v0, v[130:133] offset:128
	v_add_f32_e32 v134, v134, v60
	v_add_f32_e32 v135, v135, v61
	v_add_f32_e32 v136, v136, v62
	v_add_f32_e32 v137, v137, v63
	v_mul_f32_e32 v134, 0xbfb8aa3b, v134
	v_mul_f32_e32 v135, 0xbfb8aa3b, v135
	v_mul_f32_e32 v136, 0xbfb8aa3b, v136
	v_mul_f32_e32 v137, 0xbfb8aa3b, v137
	v_exp_f32_e32 v134, v134
	v_exp_f32_e32 v135, v135
	v_exp_f32_e32 v136, v136
	v_exp_f32_e32 v137, v137
	v_add_f32_e32 v134, 1.0, v134
	v_add_f32_e32 v135, 1.0, v135
	v_add_f32_e32 v136, 1.0, v136
	v_add_f32_e32 v137, 1.0, v137
	v_rcp_f32_e32 v134, v134
	v_rcp_f32_e32 v135, v135
	v_rcp_f32_e32 v136, v136
	v_rcp_f32_e32 v137, v137
	v_pk_mul_f32 v[134:135], v[196:197], v[134:135]
	v_pk_mul_f32 v[136:137], v[194:195], v[136:137]
	ds_write_b128 v0, v[134:137] offset:192
	s_branch .LBB0_510
